# final candidate: group barriers (census-checked) + row remap guarded on grid==256 + early L1 invalidate in grid barriers + GEMM loop edits
# speedup vs baseline: 1.0021x; 1.0021x over previous
.LBB0_47:
	s_or_b64 exec, exec, s[4:5]
	v_mov_b32_e32 v2, v0
	s_and_b32 s2, s87, 7
	s_lshl_b32 s2, s2, 5
	s_bfe_u32 s3, s87, 0x30003
	s_lshl_b32 s3, s3, 2
	s_or_b32 s2, s2, s3
	s_lshr_b32 s3, s87, 6
	s_and_b32 s3, s3, 3
	s_or_b32 s2, s2, s3
	s_cmp_eq_u32 s65, 0x100
	s_cselect_b32 s2, s2, s87
	s_lshl_b32 s2, s2, 3
	v_writelane_b32 v255, s2, 4
	s_lshl_b32 s3, s87, 3
	v_readfirstlane_b32 s2, v2
	s_ashr_i32 s14, s2, 6
	s_add_i32 s2, s14, s3
	s_cmp_lt_i32 s2, 0xb380
	s_cselect_b64 s[4:5], -1, 0
	s_cmp_gt_i32 s2, 0xb37f
	v_and_b32_e32 v4, 63, v2
	s_cbranch_scc1 .LBB0_53
	s_cmpk_lt_i32 s2, 0x2c00
	s_mov_b32 s15, s2
	s_cbranch_scc1 .LBB0_64
	s_cmpk_gt_u32 s2, 0x57ff
	s_cbranch_scc0 .LBB0_54
	s_cmpk_gt_u32 s2, 0x6dff
	s_cbranch_scc0 .LBB0_55
	s_cmpk_gt_u32 s2, 0x83ff
	s_cbranch_scc0 .LBB0_56
	s_add_i32 s15, s2, 0x8400
	s_mov_b64 s[6:7], 0
	s_branch .LBB0_57

.Lgc_e1:
	s_or_b64 exec, exec, s[4:5]
	s_waitcnt lgkmcnt(0)
	s_abs_i32 s2, s65
	v_cvt_f32_u32_e32 v1, s2
	v_cmp_eq_u32_e64 s[4:5], 0, v0
	s_ashr_i32 s3, s65, 31
	s_mov_b32 s41, 0
	v_rcp_iflag_f32_e32 v1, v1
	v_writelane_b32 v255, s4, 5
	v_mov_b32_e32 v3, 0
	s_mov_b32 s91, 0xf800000
	v_mul_f32_e32 v1, 0x4f7ffffe, v1
	v_cvt_u32_f32_e32 v1, v1
	v_writelane_b32 v255, s5, 6
	s_sub_i32 s4, 0, s2
	v_mov_b32_e32 v214, 0x260
	v_readfirstlane_b32 s5, v1
	s_mul_i32 s4, s4, s5
	s_mul_hi_u32 s4, s5, s4
	s_add_i32 s5, s5, s4
	s_mul_hi_u32 s4, s5, 0x380
	s_mul_i32 s4, s4, s2
	s_sub_i32 s4, 0x380, s4
	s_sub_i32 s5, s4, s2
	s_cmp_ge_u32 s4, s2
	s_cselect_b32 s4, s5, s4
	s_sub_i32 s5, s4, s2
	s_cmp_ge_u32 s4, s2
	s_cselect_b32 s6, s5, s4
	s_and_b32 s2, s87, 7
	s_lshl_b32 s2, s2, 5
	s_bfe_u32 s4, s87, 0x30003
	s_lshl_b32 s4, s4, 2
	s_or_b32 s2, s2, s4
	s_lshr_b32 s4, s87, 6
	s_and_b32 s4, s4, 3
	s_or_b32 s2, s2, s4
	s_cmp_eq_u32 s65, 0x100
	s_cselect_b32 s2, s2, s87
	s_lshl_b32 s2, s2, 6
	s_sub_i32 s4, s65, s6
	v_writelane_b32 v255, s2, 7
	s_lshl_b32 s5, s6, 4
	s_lshl_b32 s4, s4, 3
	s_lshl_b32 s2, s65, 3
	v_writelane_b32 v255, s4, 8
	s_sub_i32 s4, s38, s5
	v_writelane_b32 v255, s4, 9
	s_sub_i32 s4, s2, s5
	s_addk_i32 s4, 0x5000
	v_writelane_b32 v255, s4, 10
	s_lshl_b32 s4, s6, 3
	v_writelane_b32 v255, s6, 11
	s_sub_i32 s2, s2, s4
	s_ashr_i32 s39, s38, 31
	v_writelane_b32 v255, s2, 12
	s_lshl_b64 s[4:5], s[38:39], 7
	v_writelane_b32 v255, s4, 13
	s_mov_b32 s2, 1
	s_add_i32 s6, 0, 0x20000
	v_writelane_b32 v255, s5, 14
	v_writelane_b32 v255, s2, 15
	v_writelane_b32 v255, s6, 16
	s_add_i32 s6, 0, 0x20004
	v_writelane_b32 v255, s6, 17
	s_add_i32 s6, 0, 0x14800
	v_writelane_b32 v255, s6, 18
	v_writelane_b32 v255, s87, 19
	s_lshl_b32 s88, s65, 6
	s_mov_b64 s[4:5], -1
	v_mov_b32_e32 v1, 0x358637bd
	s_mov_b32 s69, 0x800000
	s_mov_b32 s81, 0x1000000
	s_mov_b32 s33, 0x1800000
	s_brev_b32 s12, 64
	s_mov_b32 s13, 0x2800000
	s_mov_b32 s60, 0x3000000
	s_movk_i32 s89, 0x1000
	s_movk_i32 s2, 0x1fff
	s_mov_b64 s[50:51], 0x4000
	v_mov_b32_e32 v254, 1
	s_movk_i32 s42, 0x2000
	s_mov_b32 s92, 0x1ffffe0
	s_movk_i32 s80, 0x1c00
	s_mov_b32 s85, 0x5040100
	s_movk_i32 s43, 0x7fff
	s_movk_i32 s84, 0xc00
	s_mov_b32 s52, 0x42b504f3
	s_mov_b32 s53, 0x3d010000
	s_mov_b32 s54, 0x3ca10000
	s_mov_b32 s55, 0x3d018000
	s_mov_b32 s56, 0x3ca18000
	s_mov_b32 s57, 0x42ddb3d8
	v_mov_b64_e32 v[196:197], 0x200
	v_mov_b32_e32 v215, 0xbf317218
	v_mov_b32_e32 v218, 0xbfb8aa3b
	v_mov_b32_e32 v219, 0xf149f2ca
	v_mov_b32_e32 v220, 0xc0000
	s_mov_b64 s[62:63], 0x10000
	s_mov_b32 s64, 0x3e0293ee
	s_mov_b32 s68, 0x3dd53b94
	s_mov_b32 s66, s41
	s_mov_b32 s16, 0
	v_writelane_b32 v255, s90, 20
	s_branch .LBB0_258

.Lgb0_spin:
	global_load_dword v250, v248, s[8:9] sc1
	s_waitcnt vmcnt(0)
	v_readfirstlane_b32 s11, v250
	s_nop 3
	s_lshl_b32 s11, s11, 2
	s_or_b32 s11, s11, 3
	s_cmp_ge_u32 s11, s32
	s_cbranch_scc1 .Lgb0_done
	s_add_i32 s10, s10, 1
	s_cmp_gt_u32 s10, 0x8000
	s_cbranch_scc1 .Lgb0_done
	s_sleep 1
	s_branch .Lgb0_spin
